# P0 prologue: batch the 8 serialized w_in/norm_g load round trips per item (and b1p loop 8x unrolled loads)
# speedup vs baseline: 1.3247x; 1.3247x over previous
; __device__ __forceinline__ unsigned pk2(float lo, float hi) { f32x2_t v = {lo, hi}; bf16x2_t b = __builtin_convertvector(v, bf16x2_t); return __builtin_bit_cast(unsigned, b); }
; __device__ __forceinline__ void p0_prologue(const Args& a, int gt, int ngt) {
;     ...
;       const int n = it % NTOT, r = it / NTOT, kc = r % (DM / 8), l = r / (DM / 8);
;       const int sc = win_srccol(n);
;       const float qs = (n < 256 || (n >= C_FQ && n < C_FQ + 256)) ? QS : 1.f;
;       float v[8];
; #pragma unroll
;       for (int j = 0; j < 8; ++j) { const int k = kc * 8 + j; v[j] = (sc < 0) ? 0.f : a.w_in[((size_t)l * DM + k) * DIN + sc] * a.norm_g[l * DM + k] * qs; }
;       u32x4 w; w.x = pk2(v[0], v[1]); w.y = pk2(v[2], v[3]); w.z = pk2(v[4], v[5]); w.w = pk2(v[6], v[7]);
;       *(u32x4*)(dst + ((size_t)l * NTOT + n) * DM + kc * 8) = w;
.LBB0_26:
	s_or_b64 exec, exec, s[2:3]
	v_lshrrev_b32_e32 v10, 25, v8
	v_add_u32_e32 v10, v8, v10
	v_and_b32_e32 v10, 0x1fffff80, v10
	v_ashrrev_i32_e32 v6, 19, v6
	v_sub_u32_e32 v10, v8, v10
	v_add_u32_e32 v8, v6, v7
	v_add_u32_e32 v6, 0xfffff980, v9
	v_cmp_gt_i32_e32 vcc, s27, v9
	v_cmp_gt_u32_e64 s[2:3], s27, v6
	s_or_b64 vcc, vcc, s[2:3]
	v_ashrrev_i32_e32 v9, 31, v8
	v_cndmask_b32_e32 v17, 1.0, v1, vcc
	v_cmp_lt_i32_e32 vcc, -1, v4
	v_max_i32_e32 v4, 0, v4
	v_lshlrev_b32_e32 v6, 3, v10
	v_lshlrev_b64 v[14:15], 10, v[8:9]
	s_waitcnt lgkmcnt(0)
	v_lshl_add_u64 v[12:13], v[4:5], 2, s[56:57]
	v_lshlrev_b32_e32 v10, 10, v8
	v_mov_b32_e32 v9, 0
	v_mov_b32_e32 v4, 0
	s_mov_b64 s[12:13], vcc
	s_mov_b64 s[2:3], exec
	s_mov_b64 s[14:15], 0x7640
	v_ashrrev_i32_e32 v11, 31, v10
	v_ashrrev_i32_e32 v7, 31, v6
	v_add_u32_e32 v18, v14, v6
	v_mul_hi_i32_i24_e32 v21, 0x7640, v18
	v_mul_i32_i24_e32 v20, 0x7640, v18
	v_lshl_add_u64 v[20:21], v[12:13], 0, v[20:21]
	v_lshl_add_u64 v[22:23], v[6:7], 0, v[10:11]
	v_lshl_add_u64 v[22:23], v[22:23], 2, s[54:55]
	global_load_dword v234, v[20:21], off
	v_lshl_add_u64 v[20:21], v[20:21], 0, s[14:15]
	global_load_dword v235, v[20:21], off
	v_lshl_add_u64 v[20:21], v[20:21], 0, s[14:15]
	global_load_dword v236, v[20:21], off
	v_lshl_add_u64 v[20:21], v[20:21], 0, s[14:15]
	global_load_dword v237, v[20:21], off
	v_lshl_add_u64 v[20:21], v[20:21], 0, s[14:15]
	global_load_dword v238, v[20:21], off
	v_lshl_add_u64 v[20:21], v[20:21], 0, s[14:15]
	global_load_dword v239, v[20:21], off
	v_lshl_add_u64 v[20:21], v[20:21], 0, s[14:15]
	global_load_dword v240, v[20:21], off
	v_lshl_add_u64 v[20:21], v[20:21], 0, s[14:15]
	global_load_dword v241, v[20:21], off
	global_load_dwordx4 v[242:245], v[22:23], off
	global_load_dwordx4 v[246:249], v[22:23], off offset:16
	s_waitcnt vmcnt(0)
	v_mul_f32_e32 v4, v234, v242
	v_mul_f32_e32 v4, v17, v4
	v_mul_f32_e32 v9, v235, v243
	v_mul_f32_e32 v9, v17, v9
	v_mul_f32_e32 v18, v236, v244
	v_mul_f32_e32 v18, v17, v18
	v_mul_f32_e32 v15, v237, v245
	v_mul_f32_e32 v15, v17, v15
	v_mul_f32_e32 v20, v238, v246
	v_mul_f32_e32 v20, v17, v20
	v_mul_f32_e32 v19, v239, v247
	v_mul_f32_e32 v19, v17, v19
	v_mul_f32_e32 v21, v240, v248
	v_mul_f32_e32 v21, v17, v21
	v_mul_f32_e32 v22, v241, v249
	v_mul_f32_e32 v22, v17, v22
	v_cndmask_b32_e64 v4, 0, v4, s[12:13]
	v_cndmask_b32_e64 v9, 0, v9, s[12:13]
	v_cndmask_b32_e64 v18, 0, v18, s[12:13]
	v_cndmask_b32_e64 v15, 0, v15, s[12:13]
	v_cndmask_b32_e64 v20, 0, v20, s[12:13]
	v_cndmask_b32_e64 v19, 0, v19, s[12:13]
	v_cndmask_b32_e64 v21, 0, v21, s[12:13]
	v_cndmask_b32_e64 v22, 0, v22, s[12:13]
	s_branch .LBB0_7

; __device__ __forceinline__ void p0_prologue(const Args& a, int gt, int ngt) {
;     ...
;     for (int o = gw; o < 512; o += ngw) {
;       const int c = o % 128, m4 = o / 128;
;       const float* w1 = a.cmp_w1 + (size_t)m4 * 2048 * 128; const float* pos = a.cmp_pos + (size_t)m4 * 2048;
;       float s = 0.f;
;       for (int kk = lane; kk < 2048; kk += 64) s += pos[kk] * w1[(size_t)kk * 128 + c];
;       s = wave_sum(s);
;       if (lane == 0) dst[o] = s + a.cmp_b1[m4 * 128 + c];
;     }
.LBB0_61:
	global_load_dword v234, v[14:15], off
	global_load_dword v235, v[14:15], off offset:256
	global_load_dword v236, v[14:15], off offset:512
	global_load_dword v237, v[14:15], off offset:768
	global_load_dword v238, v[14:15], off offset:1024
	global_load_dword v239, v[14:15], off offset:1280
	global_load_dword v240, v[14:15], off offset:1536
	global_load_dword v241, v[14:15], off offset:1792
	global_load_dword v242, v[16:17], off
	v_lshl_add_u64 v[16:17], v[16:17], 0, s[12:13]
	global_load_dword v243, v[16:17], off
	v_lshl_add_u64 v[16:17], v[16:17], 0, s[12:13]
	global_load_dword v244, v[16:17], off
	v_lshl_add_u64 v[16:17], v[16:17], 0, s[12:13]
	global_load_dword v245, v[16:17], off
	v_lshl_add_u64 v[16:17], v[16:17], 0, s[12:13]
	global_load_dword v246, v[16:17], off
	v_lshl_add_u64 v[16:17], v[16:17], 0, s[12:13]
	global_load_dword v247, v[16:17], off
	v_lshl_add_u64 v[16:17], v[16:17], 0, s[12:13]
	global_load_dword v248, v[16:17], off
	v_lshl_add_u64 v[16:17], v[16:17], 0, s[12:13]
	global_load_dword v249, v[16:17], off
	v_lshl_add_u64 v[16:17], v[16:17], 0, s[12:13]
	v_add_u32_e32 v13, 0x200, v13
	v_cmp_lt_u32_e64 s[0:1], s16, v13
	v_lshl_add_u64 v[14:15], s[10:11], 3, v[14:15]
	s_or_b64 s[14:15], s[0:1], s[14:15]
	s_waitcnt vmcnt(0)
	v_fmac_f32_e32 v11, v234, v242
	v_fmac_f32_e32 v11, v235, v243
	v_fmac_f32_e32 v11, v236, v244
	v_fmac_f32_e32 v11, v237, v245
	v_fmac_f32_e32 v11, v238, v246
	v_fmac_f32_e32 v11, v239, v247
	v_fmac_f32_e32 v11, v240, v248
	v_fmac_f32_e32 v11, v241, v249
	s_andn2_b64 exec, exec, s[14:15]
	s_cbranch_execnz .LBB0_61
	s_or_b64 exec, exec, s[14:15]
	ds_bpermute_b32 v13, v1, v11
	s_waitcnt lgkmcnt(0)
	v_add_f32_e32 v11, v11, v13
	ds_bpermute_b32 v13, v3, v11
	s_waitcnt lgkmcnt(0)
	v_add_f32_e32 v11, v11, v13
	ds_bpermute_b32 v13, v18, v11
	s_waitcnt lgkmcnt(0)
	v_add_f32_e32 v11, v11, v13
	ds_bpermute_b32 v13, v19, v11
	s_waitcnt lgkmcnt(0)
	v_add_f32_e32 v11, v11, v13
	ds_bpermute_b32 v13, v20, v11
	s_waitcnt lgkmcnt(0)
	v_add_f32_e32 v11, v11, v13
	ds_bpermute_b32 v13, v21, v11
	s_and_saveexec_b64 s[0:1], vcc
	s_cbranch_execz .LBB0_59
	v_lshl_add_u32 v14, v10, 7, v12
	v_ashrrev_i32_e32 v15, 31, v14
	v_lshl_add_u64 v[14:15], v[14:15], 2, s[64:65]
	global_load_dword v10, v[14:15], off
	s_waitcnt lgkmcnt(0)
	v_add_f32_e32 v11, v11, v13
	s_waitcnt vmcnt(0)
	v_add_f32_e32 v12, v11, v10
	v_lshl_add_u64 v[10:11], v[4:5], 2, s[6:7]
	global_store_dword v[10:11], v12, off
	s_branch .LBB0_59

; __global__ void __launch_bounds__(512, 2) hybrid_fwd(Args a) {
	.amdhsa_kernel _Z10hybrid_fwd4Args
		.amdhsa_group_segment_fixed_size 0
		.amdhsa_private_segment_fixed_size 0
		.amdhsa_kernarg_size 392
		.amdhsa_user_sgpr_count 2
		.amdhsa_user_sgpr_dispatch_ptr 0
		.amdhsa_user_sgpr_queue_ptr 0
		.amdhsa_user_sgpr_kernarg_segment_ptr 1
		.amdhsa_user_sgpr_dispatch_id 0
		.amdhsa_user_sgpr_kernarg_preload_length 0
		.amdhsa_user_sgpr_kernarg_preload_offset 0
		.amdhsa_user_sgpr_private_segment_size 0
		.amdhsa_uses_dynamic_stack 0
		.amdhsa_enable_private_segment 0
		.amdhsa_system_sgpr_workgroup_id_x 1
		.amdhsa_system_sgpr_workgroup_id_y 0
		.amdhsa_system_sgpr_workgroup_id_z 0
		.amdhsa_system_sgpr_workgroup_info 0
		.amdhsa_system_vgpr_workitem_id 2
		.amdhsa_next_free_vgpr 256
		.amdhsa_next_free_sgpr 98
		.amdhsa_accum_offset 256
		.amdhsa_reserve_vcc 1
		.amdhsa_float_round_mode_32 0
		.amdhsa_float_round_mode_16_64 0
		.amdhsa_float_denorm_mode_32 3
		.amdhsa_float_denorm_mode_16_64 3
		.amdhsa_dx10_clamp 1
		.amdhsa_ieee_mode 1
		.amdhsa_fp16_overflow 0
		.amdhsa_tg_split 0
		.amdhsa_exception_fp_ieee_invalid_op 0
		.amdhsa_exception_fp_denorm_src 0
		.amdhsa_exception_fp_ieee_div_zero 0
		.amdhsa_exception_fp_ieee_overflow 0
		.amdhsa_exception_fp_ieee_underflow 0
		.amdhsa_exception_fp_ieee_inexact 0
		.amdhsa_exception_int_div_zero 0
	.end_amdhsa_kernel

; __global__ void __launch_bounds__(512, 2) hybrid_fwd(Args a) {
amdhsa.kernels:
  - .agpr_count:     0
    .args:
      - .offset:         0
        .size:           136
        .value_kind:     by_value
      - .offset:         136
        .size:           4
        .value_kind:     hidden_block_count_x
      - .offset:         140
        .size:           4
        .value_kind:     hidden_block_count_y
      - .offset:         144
        .size:           4
        .value_kind:     hidden_block_count_z
      - .offset:         148
        .size:           2
        .value_kind:     hidden_group_size_x
      - .offset:         150
        .size:           2
        .value_kind:     hidden_group_size_y
      - .offset:         152
        .size:           2
        .value_kind:     hidden_group_size_z
      - .offset:         154
        .size:           2
        .value_kind:     hidden_remainder_x
      - .offset:         156
        .size:           2
        .value_kind:     hidden_remainder_y
      - .offset:         158
        .size:           2
        .value_kind:     hidden_remainder_z
      - .offset:         176
        .size:           8
        .value_kind:     hidden_global_offset_x
      - .offset:         184
        .size:           8
        .value_kind:     hidden_global_offset_y
      - .offset:         192
        .size:           8
        .value_kind:     hidden_global_offset_z
      - .offset:         200
        .size:           2
        .value_kind:     hidden_grid_dims
      - .offset:         224
        .size:           8
        .value_kind:     hidden_multigrid_sync_arg
      - .offset:         256
        .size:           4
        .value_kind:     hidden_dynamic_lds_size
    .group_segment_fixed_size: 0
    .kernarg_segment_align: 8
    .kernarg_segment_size: 392
    .language:       OpenCL C
    .language_version:
      - 2
      - 0
    .max_flat_workgroup_size: 512
    .name:           _Z10hybrid_fwd4Args
    .private_segment_fixed_size: 0
    .sgpr_count:     104
    .sgpr_spill_count: 3
    .symbol:         _Z10hybrid_fwd4Args.kd
    .uniform_work_group_size: 1
    .uses_dynamic_stack: false
    .vgpr_count:     256
    .vgpr_spill_count: 0
    .wavefront_size: 64
